# residual epilogue: the 8 cross-lane row-sum reductions and slot stores batched after the last row group (2 waits instead of 16, one slot base address)
# speedup vs baseline: 1.0070x; 1.0064x over previous
; __device__ __forceinline__ void epi_all_run(const void* Pk_, int l, int s, const f32x4 (&acc)[2][2][4][2], const pg8::Unit& u, int wr, int wc, int fr, int fq) {
;     ...
;         } else {
;             const float* MOD = (const float*)(ws + WS_MOD);
;             const int gidx = (s == 1) ? 2 : (s == 4 ? 5 : 8);
;             const float* base = (l == 0 && s == 1) ? A.x : A.out; float* out = A.out;
;             const float* gp = MOD + (size_t)(l * 4 + b) * NMODC + gidx * DM; const float scale = (s == 4) ? 1.0f : 0.5f;
;             const int nsite = 3 * l + (s == 1 ? 1 : (s == 4 ? 2 : 3));
;             const int col0 = u.pn * 256 + wc * 32 + 8 * fq;
;             float* slots = (float*)(ws + WS_RSP) + (size_t)nsite * M * 16;
;             f32x4 gv[2][2];
; #pragma unroll
;             for (int bj = 0; bj < 2; ++bj)
; #pragma unroll
;                 for (int n = 0; n < 2; ++n) gv[bj][n] = *(const f32x4*)(gp + col0 + bj * 128 + n * 4) * scale;
;             f32x4 bb[2][2][2];
; #pragma unroll
;             for (int bj = 0; bj < 2; ++bj)
; #pragma unroll
;                 for (int n = 0; n < 2; ++n) bb[0][bj][n] = *(const f32x4*)(base + (size_t)row0 * DM + col0 + bj * 128 + n * 4);
; #pragma unroll
;             for (int g = 0; g < 8; ++g) {
;                 const int ai = g >> 2, m = g & 3, row = row0 + ai * 128 + m * 16;
;                 if (g < 7) { const int rown = row0 + ((g + 1) >> 2) * 128 + ((g + 1) & 3) * 16;
; #pragma unroll
;                     for (int bj = 0; bj < 2; ++bj)
; #pragma unroll
;                         for (int n = 0; n < 2; ++n) bb[(g + 1) & 1][bj][n] = *(const f32x4*)(base + (size_t)rown * DM + col0 + bj * 128 + n * 4); }
;                 float ss = 0.f;
; #pragma unroll
;                 for (int bj = 0; bj < 2; ++bj)
; #pragma unroll
;                     for (int n = 0; n < 2; ++n) {
;                         const f32x4 h = bb[g & 1][bj][n] + gv[bj][n] * acc[ai][bj][m][n];
;                         *(f32x4*)(out + (size_t)row * DM + col0 + bj * 128 + n * 4) = h;
;                         ss += (h[0] * h[0] + h[1] * h[1]) + (h[2] * h[2] + h[3] * h[3]);
;                     }
;                 if (nsite < 3 * DEPTH) {
;                     ss += shx(ss, 16); ss += shx(ss, 32);
;                     if (fq == 0) __hip_atomic_store(slots + ((size_t)u.pn * M + row) * 4 + wc, ss, __ATOMIC_RELAXED, __HIP_MEMORY_SCOPE_AGENT);
.LBB0_90:
	s_andn2_b64 vcc, exec, s[46:47]
	v_or_b32_e32 v186, 16, v184
	s_cbranch_vccnz .LBB0_125
	s_ashr_i32 s20, s31, 4
	s_cmp_eq_u32 s75, 0
	s_cselect_b64 s[38:39], -1, 0
	s_cmp_eq_u32 s76, 4
	s_cselect_b64 s[46:47], -1, 0
	v_cndmask_b32_e64 v168, 0.5, 1.0, s[46:47]
	s_and_b64 s[46:47], s[46:47], exec
	s_cselect_b32 s31, s93, 0x2000
	s_cselect_b32 s50, 2, 3
	s_cmp_eq_u32 s76, 1
	s_cselect_b64 s[46:47], -1, 0
	s_and_b64 s[48:49], s[46:47], exec
	s_cselect_b32 s31, 0x800, s31
	s_cselect_b32 s48, 1, s50
	s_and_b64 s[38:39], s[38:39], s[46:47]
	s_and_b64 s[38:39], s[38:39], exec
	s_cselect_b32 s38, 0, 0xc0
	s_add_u32 s38, s4, s38
	s_addc_u32 s39, s5, 0
	s_lshl_b32 s46, s75, 2
	s_add_i32 s20, s46, s20
	s_mul_hi_i32 s46, s20, 0x9000
	s_mul_i32 s20, s20, 0x9000
	s_waitcnt lgkmcnt(0)
	s_add_u32 s20, s34, s20
	s_addc_u32 s47, s35, s46
	s_lshl_b32 s31, s31, 2
	v_lshl_or_b32 v130, s30, 8, v228
	s_add_u32 s46, s20, s31
	v_ashrrev_i32_e32 v131, 31, v130
	s_load_dwordx2 s[38:39], s[38:39], 0x0
	s_nop 0
	s_load_dwordx2 s[4:5], s[4:5], 0xc0
	s_addc_u32 s47, s47, 0
	v_lshlrev_b64 v[188:189], 2, v[130:131]
	v_lshl_add_u64 v[130:131], s[46:47], 0, v[188:189]
	s_mov_b64 s[46:47], 0x10000
	s_mov_b32 s20, 0x10000
	v_lshl_add_u64 v[132:133], v[130:131], 0, s[46:47]
	v_add_co_u32_e32 v130, vcc, s20, v130
	v_ashrrev_i32_e32 v185, 31, v184
	s_nop 0
	v_addc_co_u32_e32 v131, vcc, 0, v131, vcc
	v_lshlrev_b64 v[190:191], 12, v[184:185]
	v_ashrrev_i32_e32 v187, 31, v186
	global_load_dwordx4 v[142:145], v[130:131], off
	global_load_dwordx4 v[150:153], v[132:133], off offset:528
	global_load_dwordx4 v[154:157], v[132:133], off offset:16
	global_load_dwordx4 v[158:161], v[132:133], off offset:512
	s_waitcnt lgkmcnt(0)
	v_lshl_add_u64 v[130:131], s[38:39], 0, v[190:191]
	v_lshl_add_u64 v[206:207], s[38:39], 0, v[188:189]
	v_lshlrev_b64 v[166:167], 12, v[186:187]
	v_lshl_add_u64 v[130:131], v[130:131], 0, v[188:189]
	v_lshl_add_u64 v[134:135], v[206:207], 0, v[166:167]
	global_load_dwordx4 v[162:165], v[130:131], off
	global_load_dwordx4 v[208:211], v[130:131], off offset:16
	global_load_dwordx4 v[212:215], v[130:131], off offset:528
	global_load_dwordx4 v[230:233], v[130:131], off offset:512
	global_load_dwordx4 v[138:141], v[134:135], off offset:16
	global_load_dwordx4 v[146:149], v[134:135], off
	s_nop 0
	global_load_dwordx4 v[130:133], v[134:135], off offset:528
	s_nop 0
	global_load_dwordx4 v[134:137], v[134:135], off offset:512
	s_mul_i32 s75, s75, 3
	s_add_i32 s48, s48, s75
	s_ashr_i32 s49, s48, 31
	v_lshl_add_u64 v[200:201], s[4:5], 0, v[188:189]
	s_lshl_b64 s[4:5], s[48:49], 20
	s_add_u32 s4, s34, s4
	s_addc_u32 s5, s35, s5
	s_add_u32 s20, s4, 0xed00000
	s_addc_u32 s46, s5, 0
	v_lshl_add_u64 v[234:235], v[200:201], 0, v[190:191]
	s_cmp_lt_i32 s48, 6
	s_cselect_b64 s[38:39], -1, 0
	s_cmp_gt_i32 s48, 5
	s_waitcnt vmcnt(0)
	v_pk_mul_f32 v[202:203], v[168:169], v[144:145] op_sel_hi:[0,1]
	v_pk_mul_f32 v[204:205], v[168:169], v[142:143] op_sel_hi:[0,1]
	v_pk_mul_f32 v[198:199], v[168:169], v[156:157] op_sel_hi:[0,1]
	v_pk_mul_f32 v[196:197], v[168:169], v[154:155] op_sel_hi:[0,1]
	v_pk_mul_f32 v[192:193], v[168:169], v[160:161] op_sel_hi:[0,1]
	v_pk_mul_f32 v[194:195], v[168:169], v[158:159] op_sel_hi:[0,1]
	v_pk_mul_f32 v[190:191], v[168:169], v[152:153] op_sel_hi:[0,1]
	v_pk_mul_f32 v[188:189], v[168:169], v[150:151] op_sel_hi:[0,1]
	v_pk_fma_f32 v[128:129], v[128:129], v[202:203], v[164:165]
	v_pk_fma_f32 v[126:127], v[126:127], v[204:205], v[162:163]
	v_pk_fma_f32 v[124:125], v[124:125], v[198:199], v[210:211]
	v_pk_fma_f32 v[122:123], v[122:123], v[196:197], v[208:209]
	v_pk_fma_f32 v[120:121], v[120:121], v[192:193], v[232:233]
	v_pk_fma_f32 v[118:119], v[118:119], v[194:195], v[230:231]
	v_pk_fma_f32 v[116:117], v[116:117], v[190:191], v[214:215]
	v_pk_fma_f32 v[114:115], v[114:115], v[188:189], v[212:213]
	global_store_dwordx4 v[234:235], v[126:129], off
	global_store_dwordx4 v[234:235], v[122:125], off offset:16
	global_store_dwordx4 v[234:235], v[118:121], off offset:512
	global_store_dwordx4 v[234:235], v[114:117], off offset:528
	s_cbranch_scc1 .LBB0_95
	v_mul_f32_e32 v143, v127, v127
	v_fmac_f32_e32 v143, v126, v126
	v_mul_f32_e32 v142, v129, v129
	v_fmac_f32_e32 v142, v128, v128
	v_add_f32_e32 v142, v143, v142
	v_mul_f32_e32 v143, v123, v123
	v_mul_f32_e32 v144, v125, v125
	v_fmac_f32_e32 v143, v122, v122
	v_fmac_f32_e32 v144, v124, v124
	v_add_f32_e32 v143, v143, v144
	v_add_f32_e32 v142, v142, v143
	v_mul_f32_e32 v143, v119, v119
	v_mul_f32_e32 v144, v121, v121
	v_fmac_f32_e32 v143, v118, v118
	v_fmac_f32_e32 v144, v120, v120
	v_add_f32_e32 v143, v143, v144
	v_add_f32_e32 v142, v142, v143
	v_mul_f32_e32 v143, v115, v115
	v_mul_f32_e32 v144, v117, v117
	v_fmac_f32_e32 v143, v114, v114
	v_fmac_f32_e32 v144, v116, v116
	v_add_f32_e32 v143, v143, v144
	v_add_f32_e32 v142, v142, v143
	v_mov_b32_e32 v170, v142
; __device__ __forceinline__ float shx(float v, int o) { const int idx = (((int)otid() & 63) ^ o) << 2; return __builtin_bit_cast(float, __builtin_amdgcn_ds_bpermute(idx, __builtin_bit_cast(int, v))); }
; __device__ __forceinline__ void epi_all_run(const void* Pk_, int l, int s, const f32x4 (&acc)[2][2][4][2], const pg8::Unit& u, int wr, int wc, int fr, int fq) {
;     ...
;             for (int g = 0; g < 8; ++g) {
;                 const int ai = g >> 2, m = g & 3, row = row0 + ai * 128 + m * 16;
;                 if (g < 7) { const int rown = row0 + ((g + 1) >> 2) * 128 + ((g + 1) & 3) * 16;
; #pragma unroll
;                     for (int bj = 0; bj < 2; ++bj)
; #pragma unroll
;                         for (int n = 0; n < 2; ++n) bb[(g + 1) & 1][bj][n] = *(const f32x4*)(base + (size_t)rown * DM + col0 + bj * 128 + n * 4); }
;                 float ss = 0.f;
; #pragma unroll
;                 for (int bj = 0; bj < 2; ++bj)
; #pragma unroll
;                     for (int n = 0; n < 2; ++n) {
;                         const f32x4 h = bb[g & 1][bj][n] + gv[bj][n] * acc[ai][bj][m][n];
;                         *(f32x4*)(out + (size_t)row * DM + col0 + bj * 128 + n * 4) = h;
;                         ss += (h[0] * h[0] + h[1] * h[1]) + (h[2] * h[2] + h[3] * h[3]);
;                     }
;                 if (nsite < 3 * DEPTH) {
;                     ss += shx(ss, 16); ss += shx(ss, 32);
;                     if (fq == 0) __hip_atomic_store(slots + ((size_t)u.pn * M + row) * 4 + wc, ss, __ATOMIC_RELAXED, __HIP_MEMORY_SCOPE_AGENT);
;                 }
;             }
.LBB0_94:
.LBB0_95:
	v_or_b32_e32 v208, 32, v184
	v_ashrrev_i32_e32 v209, 31, v208
	v_lshlrev_b64 v[212:213], 12, v[208:209]
	v_lshl_add_u64 v[150:151], v[206:207], 0, v[212:213]
	global_load_dwordx4 v[154:157], v[150:151], off offset:16
	global_load_dwordx4 v[162:165], v[150:151], off
	s_waitcnt lgkmcnt(0)
	global_load_dwordx4 v[142:145], v[150:151], off offset:528
	s_nop 0
	global_load_dwordx4 v[150:153], v[150:151], off offset:512
	v_cndmask_b32_e64 v160, 0, 1, s[38:39]
	v_lshl_add_u64 v[158:159], v[200:201], 0, v[166:167]
	v_pk_fma_f32 v[112:113], v[112:113], v[202:203], v[148:149]
	v_pk_fma_f32 v[110:111], v[110:111], v[204:205], v[146:147]
	v_pk_fma_f32 v[108:109], v[108:109], v[198:199], v[140:141]
	v_pk_fma_f32 v[106:107], v[106:107], v[196:197], v[138:139]
	v_pk_fma_f32 v[104:105], v[104:105], v[192:193], v[136:137]
	v_pk_fma_f32 v[102:103], v[102:103], v[194:195], v[134:135]
	v_pk_fma_f32 v[100:101], v[100:101], v[190:191], v[132:133]
	v_pk_fma_f32 v[98:99], v[98:99], v[188:189], v[130:131]
	v_cmp_ne_u32_e64 s[4:5], 1, v160
	s_andn2_b64 vcc, exec, s[38:39]
	global_store_dwordx4 v[158:159], v[110:113], off
	global_store_dwordx4 v[158:159], v[106:109], off offset:16
	global_store_dwordx4 v[158:159], v[102:105], off offset:512
	global_store_dwordx4 v[158:159], v[98:101], off offset:528
	s_cbranch_vccnz .LBB0_99
	v_mul_f32_e32 v147, v111, v111
	v_mul_f32_e32 v139, v107, v107
	v_mul_f32_e32 v131, v99, v99
	v_fmac_f32_e32 v147, v110, v110
	v_mul_f32_e32 v146, v113, v113
	v_fmac_f32_e32 v139, v106, v106
	v_mul_f32_e32 v138, v109, v109
	v_mul_f32_e32 v135, v103, v103
	v_fmac_f32_e32 v131, v98, v98
	v_mul_f32_e32 v130, v101, v101
	v_fmac_f32_e32 v146, v112, v112
	v_fmac_f32_e32 v138, v108, v108
	v_fmac_f32_e32 v135, v102, v102
	v_mul_f32_e32 v134, v105, v105
	v_fmac_f32_e32 v130, v100, v100
	v_add_f32_e32 v146, v147, v146
	v_add_f32_e32 v138, v139, v138
	v_fmac_f32_e32 v134, v104, v104
	v_add_f32_e32 v130, v131, v130
	v_add_f32_e32 v138, v146, v138
	v_add_f32_e32 v134, v135, v134
	v_add_f32_e32 v134, v138, v134
	v_add_f32_e32 v130, v134, v130
	v_mov_b32_e32 v171, v130
.LBB0_98:
.LBB0_99:
	v_or_b32_e32 v210, 48, v184
	v_ashrrev_i32_e32 v211, 31, v210
	v_lshlrev_b64 v[214:215], 12, v[210:211]
	v_lshl_add_u64 v[134:135], v[206:207], 0, v[214:215]
	global_load_dwordx4 v[158:161], v[134:135], off offset:16
	global_load_dwordx4 v[166:169], v[134:135], off
	s_waitcnt lgkmcnt(0)
	global_load_dwordx4 v[130:133], v[134:135], off offset:528
	global_load_dwordx4 v[146:149], v[134:135], off offset:512
	v_lshl_add_u64 v[212:213], v[200:201], 0, v[212:213]
	s_waitcnt vmcnt(10)
	v_pk_fma_f32 v[96:97], v[96:97], v[202:203], v[164:165]
	v_pk_fma_f32 v[94:95], v[94:95], v[204:205], v[162:163]
	v_pk_fma_f32 v[92:93], v[92:93], v[198:199], v[156:157]
	v_pk_fma_f32 v[90:91], v[90:91], v[196:197], v[154:155]
	s_waitcnt vmcnt(8)
	v_pk_fma_f32 v[88:89], v[88:89], v[192:193], v[152:153]
	v_pk_fma_f32 v[86:87], v[86:87], v[194:195], v[150:151]
	v_pk_fma_f32 v[84:85], v[84:85], v[190:191], v[144:145]
	v_pk_fma_f32 v[82:83], v[82:83], v[188:189], v[142:143]
	s_and_b64 vcc, exec, s[4:5]
	global_store_dwordx4 v[212:213], v[94:97], off
	global_store_dwordx4 v[212:213], v[90:93], off offset:16
	global_store_dwordx4 v[212:213], v[86:89], off offset:512
	global_store_dwordx4 v[212:213], v[82:85], off offset:528
	s_cbranch_vccnz .LBB0_103
	v_mul_f32_e32 v135, v95, v95
	v_fmac_f32_e32 v135, v94, v94
	v_mul_f32_e32 v134, v97, v97
	v_fmac_f32_e32 v134, v96, v96
	v_add_f32_e32 v134, v135, v134
	v_mul_f32_e32 v135, v91, v91
	v_mul_f32_e32 v136, v93, v93
	v_fmac_f32_e32 v135, v90, v90
	v_fmac_f32_e32 v136, v92, v92
	v_add_f32_e32 v135, v135, v136
	v_add_f32_e32 v134, v134, v135
	v_mul_f32_e32 v135, v87, v87
	v_mul_f32_e32 v136, v89, v89
	v_fmac_f32_e32 v135, v86, v86
	v_fmac_f32_e32 v136, v88, v88
	v_add_f32_e32 v135, v135, v136
	v_add_f32_e32 v134, v134, v135
	v_mul_f32_e32 v135, v83, v83
	v_mul_f32_e32 v136, v85, v85
	v_fmac_f32_e32 v135, v82, v82
	v_fmac_f32_e32 v136, v84, v84
	v_add_f32_e32 v135, v135, v136
	v_add_f32_e32 v134, v134, v135
	v_mov_b32_e32 v172, v134
.LBB0_102:
.LBB0_103:
	v_add_u32_e32 v208, 0x80, v184
	v_ashrrev_i32_e32 v209, 31, v208
	v_lshlrev_b64 v[212:213], 12, v[208:209]
	v_lshl_add_u64 v[138:139], v[206:207], 0, v[212:213]
	global_load_dwordx4 v[150:153], v[138:139], off offset:16
	global_load_dwordx4 v[162:165], v[138:139], off
	s_waitcnt lgkmcnt(0)
	global_load_dwordx4 v[134:137], v[138:139], off offset:528
	s_nop 0
	global_load_dwordx4 v[138:141], v[138:139], off offset:512
	v_lshl_add_u64 v[214:215], v[200:201], 0, v[214:215]
	s_waitcnt vmcnt(10)
	v_pk_fma_f32 v[80:81], v[80:81], v[202:203], v[168:169]
	v_pk_fma_f32 v[78:79], v[78:79], v[204:205], v[166:167]
	v_pk_fma_f32 v[76:77], v[76:77], v[198:199], v[160:161]
	v_pk_fma_f32 v[74:75], v[74:75], v[196:197], v[158:159]
	s_waitcnt vmcnt(8)
	v_pk_fma_f32 v[72:73], v[72:73], v[192:193], v[148:149]
	v_pk_fma_f32 v[70:71], v[70:71], v[194:195], v[146:147]
	v_pk_fma_f32 v[68:69], v[68:69], v[190:191], v[132:133]
	v_pk_fma_f32 v[66:67], v[66:67], v[188:189], v[130:131]
	s_and_b64 vcc, exec, s[4:5]
	global_store_dwordx4 v[214:215], v[78:81], off
	global_store_dwordx4 v[214:215], v[74:77], off offset:16
	global_store_dwordx4 v[214:215], v[70:73], off offset:512
	global_store_dwordx4 v[214:215], v[66:69], off offset:528
	s_cbranch_vccnz .LBB0_107
	v_mul_f32_e32 v143, v79, v79
	v_fmac_f32_e32 v143, v78, v78
	v_mul_f32_e32 v142, v81, v81
	v_fmac_f32_e32 v142, v80, v80
	v_add_f32_e32 v142, v143, v142
	v_mul_f32_e32 v143, v75, v75
	v_mul_f32_e32 v144, v77, v77
	v_fmac_f32_e32 v143, v74, v74
	v_fmac_f32_e32 v144, v76, v76
	v_mul_f32_e32 v131, v67, v67
	v_add_f32_e32 v143, v143, v144
	v_fmac_f32_e32 v131, v66, v66
	v_mul_f32_e32 v130, v69, v69
	v_add_f32_e32 v142, v142, v143
	v_mul_f32_e32 v143, v71, v71
	v_mul_f32_e32 v144, v73, v73
	v_fmac_f32_e32 v130, v68, v68
	v_fmac_f32_e32 v143, v70, v70
	v_fmac_f32_e32 v144, v72, v72
	v_add_f32_e32 v130, v131, v130
	v_add_f32_e32 v143, v143, v144
	v_add_f32_e32 v142, v142, v143
	v_add_f32_e32 v130, v142, v130
	v_mov_b32_e32 v173, v130
; __device__ __forceinline__ float shx(float v, int o) { const int idx = (((int)otid() & 63) ^ o) << 2; return __builtin_bit_cast(float, __builtin_amdgcn_ds_bpermute(idx, __builtin_bit_cast(int, v))); }
; __device__ __forceinline__ void epi_all_run(const void* Pk_, int l, int s, const f32x4 (&acc)[2][2][4][2], const pg8::Unit& u, int wr, int wc, int fr, int fq) {
;     ...
;             for (int g = 0; g < 8; ++g) {
;                 const int ai = g >> 2, m = g & 3, row = row0 + ai * 128 + m * 16;
;                 if (g < 7) { const int rown = row0 + ((g + 1) >> 2) * 128 + ((g + 1) & 3) * 16;
; #pragma unroll
;                     for (int bj = 0; bj < 2; ++bj)
; #pragma unroll
;                         for (int n = 0; n < 2; ++n) bb[(g + 1) & 1][bj][n] = *(const f32x4*)(base + (size_t)rown * DM + col0 + bj * 128 + n * 4); }
;                 float ss = 0.f;
; #pragma unroll
;                 for (int bj = 0; bj < 2; ++bj)
; #pragma unroll
;                     for (int n = 0; n < 2; ++n) {
;                         const f32x4 h = bb[g & 1][bj][n] + gv[bj][n] * acc[ai][bj][m][n];
;                         *(f32x4*)(out + (size_t)row * DM + col0 + bj * 128 + n * 4) = h;
;                         ss += (h[0] * h[0] + h[1] * h[1]) + (h[2] * h[2] + h[3] * h[3]);
;                     }
;                 if (nsite < 3 * DEPTH) {
;                     ss += shx(ss, 16); ss += shx(ss, 32);
;                     if (fq == 0) __hip_atomic_store(slots + ((size_t)u.pn * M + row) * 4 + wc, ss, __ATOMIC_RELAXED, __HIP_MEMORY_SCOPE_AGENT);
;                 }
;             }
.LBB0_106:
.LBB0_107:
	v_or_b32_e32 v210, 16, v208
	v_ashrrev_i32_e32 v211, 31, v210
	v_lshlrev_b64 v[214:215], 12, v[210:211]
	v_lshl_add_u64 v[142:143], v[206:207], 0, v[214:215]
	global_load_dwordx4 v[154:157], v[142:143], off offset:16
	global_load_dwordx4 v[166:169], v[142:143], off
	s_waitcnt lgkmcnt(0)
	global_load_dwordx4 v[130:133], v[142:143], off offset:528
	s_nop 0
	global_load_dwordx4 v[142:145], v[142:143], off offset:512
	v_lshl_add_u64 v[158:159], v[200:201], 0, v[212:213]
	s_waitcnt vmcnt(10)
	v_pk_fma_f32 v[64:65], v[64:65], v[202:203], v[164:165]
	v_pk_fma_f32 v[62:63], v[62:63], v[204:205], v[162:163]
	v_pk_fma_f32 v[60:61], v[60:61], v[198:199], v[152:153]
	v_pk_fma_f32 v[58:59], v[58:59], v[196:197], v[150:151]
	s_waitcnt vmcnt(8)
	v_pk_fma_f32 v[56:57], v[56:57], v[192:193], v[140:141]
	v_pk_fma_f32 v[54:55], v[54:55], v[194:195], v[138:139]
	v_pk_fma_f32 v[52:53], v[52:53], v[190:191], v[136:137]
	v_pk_fma_f32 v[50:51], v[50:51], v[188:189], v[134:135]
	s_and_b64 vcc, exec, s[4:5]
	global_store_dwordx4 v[158:159], v[62:65], off
	global_store_dwordx4 v[158:159], v[58:61], off offset:16
	global_store_dwordx4 v[158:159], v[54:57], off offset:512
	global_store_dwordx4 v[158:159], v[50:53], off offset:528
	s_cbranch_vccnz .LBB0_111
	v_mul_f32_e32 v147, v63, v63
	v_fmac_f32_e32 v147, v62, v62
	v_mul_f32_e32 v146, v65, v65
	v_fmac_f32_e32 v146, v64, v64
	v_mul_f32_e32 v135, v51, v51
	v_add_f32_e32 v146, v147, v146
	v_mul_f32_e32 v147, v59, v59
	v_mul_f32_e32 v148, v61, v61
	v_mul_f32_e32 v139, v55, v55
	v_fmac_f32_e32 v135, v50, v50
	v_mul_f32_e32 v134, v53, v53
	v_fmac_f32_e32 v147, v58, v58
	v_fmac_f32_e32 v148, v60, v60
	v_fmac_f32_e32 v139, v54, v54
	v_mul_f32_e32 v138, v57, v57
	v_fmac_f32_e32 v134, v52, v52
	v_add_f32_e32 v147, v147, v148
	v_fmac_f32_e32 v138, v56, v56
	v_add_f32_e32 v134, v135, v134
	v_add_f32_e32 v146, v146, v147
	v_add_f32_e32 v138, v139, v138
	v_add_f32_e32 v138, v146, v138
	v_add_f32_e32 v134, v138, v134
	v_mov_b32_e32 v174, v134
.LBB0_110:
.LBB0_111:
	v_or_b32_e32 v162, 32, v208
	v_ashrrev_i32_e32 v163, 31, v162
	v_lshlrev_b64 v[212:213], 12, v[162:163]
	v_lshl_add_u64 v[138:139], v[206:207], 0, v[212:213]
	global_load_dwordx4 v[146:149], v[138:139], off offset:16
	global_load_dwordx4 v[158:161], v[138:139], off
	s_waitcnt lgkmcnt(0)
	global_load_dwordx4 v[134:137], v[138:139], off offset:528
	s_nop 0
	global_load_dwordx4 v[138:141], v[138:139], off offset:512
	v_lshl_add_u64 v[164:165], v[200:201], 0, v[214:215]
	s_waitcnt vmcnt(10)
	v_pk_fma_f32 v[48:49], v[48:49], v[202:203], v[168:169]
	v_pk_fma_f32 v[46:47], v[46:47], v[204:205], v[166:167]
	v_pk_fma_f32 v[44:45], v[44:45], v[198:199], v[156:157]
	v_pk_fma_f32 v[42:43], v[42:43], v[196:197], v[154:155]
	s_waitcnt vmcnt(8)
	v_pk_fma_f32 v[40:41], v[40:41], v[192:193], v[144:145]
	v_pk_fma_f32 v[38:39], v[38:39], v[194:195], v[142:143]
	v_pk_fma_f32 v[36:37], v[36:37], v[190:191], v[132:133]
	v_pk_fma_f32 v[34:35], v[34:35], v[188:189], v[130:131]
	s_and_b64 vcc, exec, s[4:5]
	global_store_dwordx4 v[164:165], v[46:49], off
	global_store_dwordx4 v[164:165], v[42:45], off offset:16
	global_store_dwordx4 v[164:165], v[38:41], off offset:512
	global_store_dwordx4 v[164:165], v[34:37], off offset:528
	s_cbranch_vccnz .LBB0_115
	v_mul_f32_e32 v151, v47, v47
	v_fmac_f32_e32 v151, v46, v46
	v_mul_f32_e32 v150, v49, v49
	v_fmac_f32_e32 v150, v48, v48
	v_mul_f32_e32 v131, v35, v35
	v_add_f32_e32 v150, v151, v150
	v_mul_f32_e32 v151, v43, v43
	v_mul_f32_e32 v152, v45, v45
	v_mul_f32_e32 v143, v39, v39
	v_fmac_f32_e32 v131, v34, v34
	v_mul_f32_e32 v130, v37, v37
	v_fmac_f32_e32 v151, v42, v42
	v_fmac_f32_e32 v152, v44, v44
	v_fmac_f32_e32 v143, v38, v38
	v_mul_f32_e32 v142, v41, v41
	v_fmac_f32_e32 v130, v36, v36
	v_add_f32_e32 v151, v151, v152
	v_fmac_f32_e32 v142, v40, v40
	v_add_f32_e32 v130, v131, v130
	v_add_f32_e32 v150, v150, v151
	v_add_f32_e32 v142, v143, v142
	v_add_f32_e32 v142, v150, v142
	v_add_f32_e32 v130, v142, v130
	v_mov_b32_e32 v175, v130
; __device__ __forceinline__ float shx(float v, int o) { const int idx = (((int)otid() & 63) ^ o) << 2; return __builtin_bit_cast(float, __builtin_amdgcn_ds_bpermute(idx, __builtin_bit_cast(int, v))); }
; __device__ __forceinline__ void epi_all_run(const void* Pk_, int l, int s, const f32x4 (&acc)[2][2][4][2], const pg8::Unit& u, int wr, int wc, int fr, int fq) {
;     ...
;             for (int g = 0; g < 8; ++g) {
;                 const int ai = g >> 2, m = g & 3, row = row0 + ai * 128 + m * 16;
;                 if (g < 7) { const int rown = row0 + ((g + 1) >> 2) * 128 + ((g + 1) & 3) * 16;
; #pragma unroll
;                     for (int bj = 0; bj < 2; ++bj)
; #pragma unroll
;                         for (int n = 0; n < 2; ++n) bb[(g + 1) & 1][bj][n] = *(const f32x4*)(base + (size_t)rown * DM + col0 + bj * 128 + n * 4); }
;                 float ss = 0.f;
; #pragma unroll
;                 for (int bj = 0; bj < 2; ++bj)
; #pragma unroll
;                     for (int n = 0; n < 2; ++n) {
;                         const f32x4 h = bb[g & 1][bj][n] + gv[bj][n] * acc[ai][bj][m][n];
;                         *(f32x4*)(out + (size_t)row * DM + col0 + bj * 128 + n * 4) = h;
;                         ss += (h[0] * h[0] + h[1] * h[1]) + (h[2] * h[2] + h[3] * h[3]);
;                     }
;                 if (nsite < 3 * DEPTH) {
;                     ss += shx(ss, 16); ss += shx(ss, 32);
;                     if (fq == 0) __hip_atomic_store(slots + ((size_t)u.pn * M + row) * 4 + wc, ss, __ATOMIC_RELAXED, __HIP_MEMORY_SCOPE_AGENT);
;                 }
;             }
.LBB0_114:
.LBB0_115:
	v_or_b32_e32 v164, 48, v208
	v_ashrrev_i32_e32 v165, 31, v164
	v_lshlrev_b64 v[166:167], 12, v[164:165]
	v_lshl_add_u64 v[142:143], v[206:207], 0, v[166:167]
	global_load_dwordx4 v[150:153], v[142:143], off offset:16
	global_load_dwordx4 v[154:157], v[142:143], off
	s_waitcnt lgkmcnt(0)
	global_load_dwordx4 v[130:133], v[142:143], off offset:528
	s_nop 0
	global_load_dwordx4 v[142:145], v[142:143], off offset:512
	v_lshl_add_u64 v[168:169], v[200:201], 0, v[212:213]
	s_waitcnt vmcnt(10)
	v_pk_fma_f32 v[32:33], v[32:33], v[202:203], v[160:161]
	v_pk_fma_f32 v[30:31], v[30:31], v[204:205], v[158:159]
	v_pk_fma_f32 v[28:29], v[28:29], v[198:199], v[148:149]
	v_pk_fma_f32 v[26:27], v[26:27], v[196:197], v[146:147]
	s_waitcnt vmcnt(8)
	v_pk_fma_f32 v[24:25], v[24:25], v[192:193], v[140:141]
	v_pk_fma_f32 v[22:23], v[22:23], v[194:195], v[138:139]
	v_pk_fma_f32 v[20:21], v[20:21], v[190:191], v[136:137]
	v_pk_fma_f32 v[18:19], v[18:19], v[188:189], v[134:135]
	s_and_b64 vcc, exec, s[4:5]
	global_store_dwordx4 v[168:169], v[30:33], off
	global_store_dwordx4 v[168:169], v[26:29], off offset:16
	global_store_dwordx4 v[168:169], v[22:25], off offset:512
	global_store_dwordx4 v[168:169], v[18:21], off offset:528
	s_cbranch_vccnz .LBB0_119
	v_mul_f32_e32 v159, v31, v31
	v_mul_f32_e32 v147, v27, v27
	v_mul_f32_e32 v135, v19, v19
	v_fmac_f32_e32 v159, v30, v30
	v_mul_f32_e32 v158, v33, v33
	v_fmac_f32_e32 v147, v26, v26
	v_mul_f32_e32 v146, v29, v29
	v_mul_f32_e32 v139, v23, v23
	v_fmac_f32_e32 v135, v18, v18
	v_mul_f32_e32 v134, v21, v21
	v_fmac_f32_e32 v158, v32, v32
	v_fmac_f32_e32 v146, v28, v28
	v_fmac_f32_e32 v139, v22, v22
	v_mul_f32_e32 v138, v25, v25
	v_fmac_f32_e32 v134, v20, v20
	v_add_f32_e32 v158, v159, v158
	v_add_f32_e32 v146, v147, v146
	v_fmac_f32_e32 v138, v24, v24
	v_add_f32_e32 v134, v135, v134
	v_add_f32_e32 v146, v158, v146
	v_add_f32_e32 v138, v139, v138
	v_add_f32_e32 v138, v146, v138
	v_add_f32_e32 v134, v138, v134
	v_mov_b32_e32 v176, v134
.LBB0_118:
.LBB0_119:
	v_lshl_add_u64 v[146:147], v[200:201], 0, v[166:167]
	s_waitcnt vmcnt(6)
	v_pk_fma_f32 v[16:17], v[16:17], v[202:203], v[156:157]
	s_waitcnt lgkmcnt(0)
	v_pk_fma_f32 v[14:15], v[14:15], v[204:205], v[154:155]
	v_pk_fma_f32 v[12:13], v[12:13], v[198:199], v[152:153]
	v_pk_fma_f32 v[10:11], v[10:11], v[196:197], v[150:151]
	s_waitcnt vmcnt(4)
	v_pk_fma_f32 v[8:9], v[8:9], v[192:193], v[144:145]
	v_pk_fma_f32 v[6:7], v[6:7], v[194:195], v[142:143]
	v_pk_fma_f32 v[4:5], v[4:5], v[190:191], v[132:133]
	v_pk_fma_f32 v[2:3], v[2:3], v[188:189], v[130:131]
	s_and_b64 vcc, exec, s[4:5]
	global_store_dwordx4 v[146:147], v[14:17], off
	global_store_dwordx4 v[146:147], v[10:13], off offset:16
	global_store_dwordx4 v[146:147], v[6:9], off offset:512
	global_store_dwordx4 v[146:147], v[2:5], off offset:528
	s_cbranch_vccnz .LBB0_123
	v_mul_f32_e32 v135, v15, v15
	v_fmac_f32_e32 v135, v14, v14
	v_mul_f32_e32 v134, v17, v17
	v_fmac_f32_e32 v134, v16, v16
	v_add_f32_e32 v134, v135, v134
	v_mul_f32_e32 v135, v11, v11
	v_mul_f32_e32 v136, v13, v13
	v_fmac_f32_e32 v135, v10, v10
	v_fmac_f32_e32 v136, v12, v12
	v_mul_f32_e32 v131, v3, v3
	v_add_f32_e32 v135, v135, v136
	v_fmac_f32_e32 v131, v2, v2
	v_mul_f32_e32 v130, v5, v5
	v_add_f32_e32 v134, v134, v135
	v_mul_f32_e32 v135, v7, v7
	v_mul_f32_e32 v136, v9, v9
	v_fmac_f32_e32 v130, v4, v4
	v_fmac_f32_e32 v135, v6, v6
	v_fmac_f32_e32 v136, v8, v8
	v_add_f32_e32 v130, v131, v130
	v_add_f32_e32 v135, v135, v136
	v_add_f32_e32 v134, v134, v135
	v_add_f32_e32 v130, v134, v130
	v_mov_b32_e32 v177, v130
.LBB0_122:
	v_lshlrev_b32_e32 v138, 2, v179
	v_lshlrev_b32_e32 v139, 2, v179
	s_ashr_i32 s31, s30, 31
	v_bitop3_b32 v138, v138, 64, v220 bitop3:0x6c
	v_bitop3_b32 v139, v139, s33, v220 bitop3:0x6c
	s_lshl_b64 s[48:49], s[30:31], 18
	ds_bpermute_b32 v130, v138, v170
	ds_bpermute_b32 v131, v138, v171
	ds_bpermute_b32 v132, v138, v172
	ds_bpermute_b32 v133, v138, v173
	ds_bpermute_b32 v134, v138, v174
	ds_bpermute_b32 v135, v138, v175
	ds_bpermute_b32 v136, v138, v176
	ds_bpermute_b32 v137, v138, v177
	s_add_u32 s48, s20, s48
	s_addc_u32 s49, s46, s49
	s_lshl_b32 s31, s64, 2
	s_add_u32 s48, s48, s31
	s_addc_u32 s49, s49, 0
	v_lshl_add_u64 v[140:141], v[184:185], 4, s[48:49]
	v_writelane_b32 v237, s30, 58
	s_waitcnt lgkmcnt(0)
	v_add_f32_e32 v170, v170, v130
	v_add_f32_e32 v171, v171, v131
	v_add_f32_e32 v172, v172, v132
	v_add_f32_e32 v173, v173, v133
	v_add_f32_e32 v174, v174, v134
	v_add_f32_e32 v175, v175, v135
	v_add_f32_e32 v176, v176, v136
	v_add_f32_e32 v177, v177, v137
	ds_bpermute_b32 v130, v139, v170
	ds_bpermute_b32 v131, v139, v171
	ds_bpermute_b32 v132, v139, v172
	ds_bpermute_b32 v133, v139, v173
	ds_bpermute_b32 v134, v139, v174
	ds_bpermute_b32 v135, v139, v175
	ds_bpermute_b32 v136, v139, v176
	ds_bpermute_b32 v137, v139, v177
	s_waitcnt lgkmcnt(0)
	v_add_f32_e32 v170, v170, v130
	v_add_f32_e32 v171, v171, v131
	v_add_f32_e32 v172, v172, v132
	v_add_f32_e32 v173, v173, v133
	v_add_f32_e32 v174, v174, v134
	v_add_f32_e32 v175, v175, v135
	v_add_f32_e32 v176, v176, v136
	v_add_f32_e32 v177, v177, v137
	s_and_saveexec_b64 s[4:5], s[42:43]
	global_store_dword v[140:141], v170, off sc1
	global_store_dword v[140:141], v171, off offset:256 sc1
	global_store_dword v[140:141], v172, off offset:512 sc1
	global_store_dword v[140:141], v173, off offset:768 sc1
	global_store_dword v[140:141], v174, off offset:2048 sc1
	global_store_dword v[140:141], v175, off offset:2304 sc1
	global_store_dword v[140:141], v176, off offset:2560 sc1
	global_store_dword v[140:141], v177, off offset:2816 sc1
	s_or_b64 exec, exec, s[4:5]
